# speedup vs baseline: 1.0009x; 1.0009x over previous
; #define SLOAD_(S, k0) do { vs##S##0 = *(const bf16x8*)(Vh + (long)((k0) + sr) * LDK + sc); vs##S##1 = *(const bf16x8*)(Vh + (long)((k0) + 32 + sr) * LDK + sc); \
;     ks##S##0 = *(const bf16x8*)(Kh + (long)((k0) + sr) * LDK + sc); ks##S##1 = *(const bf16x8*)(Kh + (long)((k0) + 32 + sr) * LDK + sc); } while (0)
; #define SWRITE_(S, bb) do { *(bf16x8*)(V_lds + (bb) * SHM_V + vst0) = vs##S##0; *(bf16x8*)(V_lds + (bb) * SHM_V + vst1) = vs##S##1; const int kc = sc * 2; \
;     *(bf16x8*)(K_lds + (bb) * SHM_K + KSWZ(sr, kc)) = ks##S##0; *(bf16x8*)(K_lds + (bb) * SHM_K + KSWZ(32 + sr, kc)) = ks##S##1; } while (0)
; __device__ __forceinline__ void attn_item(const u16* __restrict__ qkv, u16* __restrict__ outp, const float* __restrict__ subln,
;                                           const float* __restrict__ QN, int b, int h, int qb, float lam, char* lds) {
;     ...
;   for (int i = 0; i < ntl; i += 2) {
;     if (i + 2 < ntl) SLOAD_(A, TILE_OF(i + 2) * 64);
;     TILE_BODY(TILE_OF(i), 0);
;     if (i + 1 < ntl) SWRITE_(B, 1);
;     __syncthreads();
;     if (i + 1 >= ntl) break;
;     if (i + 3 < ntl) SLOAD_(B, TILE_OF(i + 3) * 64);
;     TILE_BODY(TILE_OF(i + 1), 1);
;     if (i + 2 < ntl) SWRITE_(A, 0);
;     __syncthreads();
;   }
.LBB0_297:
	s_and_b64 vcc, exec, s[4:5]
	s_cbranch_vccnz .LBB0_318

; #define SLOAD_(S, k0) do { vs##S##0 = *(const bf16x8*)(Vh + (long)((k0) + sr) * LDK + sc); vs##S##1 = *(const bf16x8*)(Vh + (long)((k0) + 32 + sr) * LDK + sc); \
;     ks##S##0 = *(const bf16x8*)(Kh + (long)((k0) + sr) * LDK + sc); ks##S##1 = *(const bf16x8*)(Kh + (long)((k0) + 32 + sr) * LDK + sc); } while (0)
; #define SWRITE_(S, bb) do { *(bf16x8*)(V_lds + (bb) * SHM_V + vst0) = vs##S##0; *(bf16x8*)(V_lds + (bb) * SHM_V + vst1) = vs##S##1; const int kc = sc * 2; \
;     *(bf16x8*)(K_lds + (bb) * SHM_K + KSWZ(sr, kc)) = ks##S##0; *(bf16x8*)(K_lds + (bb) * SHM_K + KSWZ(32 + sr, kc)) = ks##S##1; } while (0)
; __device__ __forceinline__ void attn_item(const u16* __restrict__ qkv, u16* __restrict__ outp, const float* __restrict__ subln,
;                                           const float* __restrict__ QN, int b, int h, int qb, float lam, char* lds) {
;     ...
;   for (int i = 0; i < ntl; i += 2) {
;     if (i + 2 < ntl) SLOAD_(A, TILE_OF(i + 2) * 64);
;     TILE_BODY(TILE_OF(i), 0);
;     if (i + 1 < ntl) SWRITE_(B, 1);
;     __syncthreads();
;     if (i + 1 >= ntl) break;
;     if (i + 3 < ntl) SLOAD_(B, TILE_OF(i + 3) * 64);
;     TILE_BODY(TILE_OF(i + 1), 1);
;     if (i + 2 < ntl) SWRITE_(A, 0);
.LBB0_300:
	s_andn2_b64 vcc, exec, s[4:5]
	s_cbranch_vccnz .LBB0_302
	s_waitcnt vmcnt(0)
	s_add_i32 s75, s13, s73
